# final variant with the GEMM1 code touch four iterations before the loop end instead of two
# baseline (speedup 1.0000x reference)
.LBB0_242:
	s_add_u32 s4, s0, 0xfffc0080
	s_addc_u32 s5, s1, -1
	s_add_i32 vcc_lo, 0, 0x10000
	v_add_u32_e32 v128, vcc_lo, v162
	ds_read_b128 v[142:145], v128
	ds_read_b128 v[146:149], v128 offset:1024
	ds_read_b128 v[150:153], v128 offset:2048
	ds_read_b128 v[154:157], v128 offset:3072
	s_cmp_eq_u32 s75, 12
	s_cselect_b32 s37, s22, s5
	s_cselect_b32 s36, s23, s4
	s_cselect_b32 s5, s7, s39
	s_cselect_b32 s4, s25, s38
	v_lshl_add_u64 v[196:197], s[0:1], 0, v[138:139]
	s_add_i32 m0, s95, 0xc000
	ds_read_b128 v[164:167], v163
	ds_read_b128 v[168:171], v163 offset:1024
	ds_read_b128 v[172:175], v163 offset:2048
	ds_read_b128 v[176:179], v163 offset:3072
	ds_read_b128 v[180:183], v163 offset:4096
	ds_read_b128 v[184:187], v163 offset:5120
	ds_read_b128 v[188:191], v163 offset:6144
	ds_read_b128 v[192:195], v163 offset:7168
	global_load_lds_dwordx4 v[196:197], off
	v_lshl_add_u64 v[196:197], s[0:1], 0, v[140:141]
	s_add_i32 m0, s95, 0xe000
	s_nop 0
	global_load_lds_dwordx4 v[196:197], off
	s_cmp_eq_u32 s75, 6
	s_cbranch_scc0 .Lct_skip
	global_load_dword v248, v[246:247], off
